# v83 + K-loop end bookkeeping (counter, pointer increments, compare) hoisted from behind the last barrier into the last MFMA block
# speedup vs baseline: 1.0134x; 1.0134x over previous
.Lbal_last_21:
	ds_read_b128 v[184:187], v153 offset:49152
	ds_read_b128 v[188:191], v153 offset:50176
	ds_read_b128 v[192:195], v153 offset:51200
	ds_read_b128 v[196:199], v153 offset:52224
	ds_read_b128 v[200:203], v153 offset:53248
	ds_read_b128 v[208:211], v153 offset:54272
	ds_read_b128 v[212:215], v153 offset:55296
	ds_read_b128 v[216:219], v153 offset:56320
	s_waitcnt vmcnt(6)
	s_waitcnt lgkmcnt(0)
	s_barrier
	s_waitcnt lgkmcnt(0)
	v_mfma_f32_16x16x32_bf16 v[60:63], v[144:147], v[184:187], v[60:63]
	v_mfma_f32_16x16x32_bf16 v[56:59], v[160:163], v[184:187], v[56:59]
	v_mfma_f32_16x16x32_bf16 v[44:47], v[144:147], v[192:195], v[44:47]
	v_mfma_f32_16x16x32_bf16 v[40:43], v[160:163], v[192:195], v[40:43]
	s_add_i32 s55, s55, 2
	s_add_u32 s53, s53, 0x100
	s_addc_u32 s54, s54, 0
	s_add_u32 s24, s24, 0x100
	s_addc_u32 s25, s25, 0
	s_cmp_gt_u32 s55, 13
	v_mfma_f32_16x16x32_bf16 v[28:31], v[144:147], v[200:203], v[28:31]
	v_mfma_f32_16x16x32_bf16 v[24:27], v[160:163], v[200:203], v[24:27]
	v_mfma_f32_16x16x32_bf16 v[12:15], v[144:147], v[212:215], v[12:15]
	v_mfma_f32_16x16x32_bf16 v[8:11], v[160:163], v[212:215], v[8:11]
	v_mfma_f32_16x16x32_bf16 v[60:63], v[156:159], v[188:191], v[60:63]
	v_mfma_f32_16x16x32_bf16 v[56:59], v[164:167], v[188:191], v[56:59]
	v_mfma_f32_16x16x32_bf16 v[44:47], v[156:159], v[196:199], v[44:47]
	v_mfma_f32_16x16x32_bf16 v[40:43], v[164:167], v[196:199], v[40:43]
	v_mfma_f32_16x16x32_bf16 v[28:31], v[156:159], v[208:211], v[28:31]
	v_mfma_f32_16x16x32_bf16 v[24:27], v[164:167], v[208:211], v[24:27]
	v_mfma_f32_16x16x32_bf16 v[12:15], v[156:159], v[216:219], v[12:15]
	v_mfma_f32_16x16x32_bf16 v[8:11], v[164:167], v[216:219], v[8:11]
	v_mfma_f32_16x16x32_bf16 v[52:55], v[168:171], v[184:187], v[52:55]
	v_mfma_f32_16x16x32_bf16 v[48:51], v[176:179], v[184:187], v[48:51]
	v_mfma_f32_16x16x32_bf16 v[36:39], v[168:171], v[192:195], v[36:39]
	v_mfma_f32_16x16x32_bf16 v[32:35], v[176:179], v[192:195], v[32:35]
	v_mfma_f32_16x16x32_bf16 v[20:23], v[168:171], v[200:203], v[20:23]
	v_mfma_f32_16x16x32_bf16 v[16:19], v[176:179], v[200:203], v[16:19]
	v_mfma_f32_16x16x32_bf16 v[4:7], v[168:171], v[212:215], v[4:7]
	v_mfma_f32_16x16x32_bf16 v[0:3], v[176:179], v[212:215], v[0:3]
	v_mfma_f32_16x16x32_bf16 v[52:55], v[172:175], v[188:191], v[52:55]
	v_mfma_f32_16x16x32_bf16 v[48:51], v[180:183], v[188:191], v[48:51]
	v_mfma_f32_16x16x32_bf16 v[36:39], v[172:175], v[196:199], v[36:39]
	v_mfma_f32_16x16x32_bf16 v[32:35], v[180:183], v[196:199], v[32:35]
	v_mfma_f32_16x16x32_bf16 v[20:23], v[172:175], v[208:211], v[20:23]
	v_mfma_f32_16x16x32_bf16 v[16:19], v[180:183], v[208:211], v[16:19]
	v_mfma_f32_16x16x32_bf16 v[4:7], v[172:175], v[216:219], v[4:7]
	v_mfma_f32_16x16x32_bf16 v[0:3], v[180:183], v[216:219], v[0:3]
	s_barrier
	s_cbranch_scc0 .LBB0_163
	s_setprio 0
	s_and_b64 vcc, exec, s[14:15]
	s_cbranch_vccz .LBB0_166
	s_barrier

.Lbal_last_20:
	ds_read_b128 v[178:181], v149 offset:49152
	ds_read_b128 v[182:185], v149 offset:50176
	ds_read_b128 v[186:189], v149 offset:51200
	ds_read_b128 v[190:193], v149 offset:52224
	ds_read_b128 v[194:197], v149 offset:53248
	ds_read_b128 v[198:201], v149 offset:54272
	ds_read_b128 v[202:205], v149 offset:55296
	ds_read_b128 v[208:211], v149 offset:56320
	s_waitcnt vmcnt(6)
	s_waitcnt lgkmcnt(0)
	s_barrier
	s_waitcnt lgkmcnt(0)
	v_mfma_f32_16x16x32_bf16 v[60:63], v[140:143], v[178:181], v[60:63]
	v_mfma_f32_16x16x32_bf16 v[56:59], v[154:157], v[178:181], v[56:59]
	v_mfma_f32_16x16x32_bf16 v[44:47], v[140:143], v[186:189], v[44:47]
	v_mfma_f32_16x16x32_bf16 v[40:43], v[154:157], v[186:189], v[40:43]
	s_add_i32 s58, s58, 2
	s_add_u32 s56, s56, 0x100
	s_addc_u32 s57, s57, 0
	s_cmp_gt_u32 s58, 13
	s_mov_b64 s[28:29], s[30:31]
	v_mfma_f32_16x16x32_bf16 v[28:31], v[140:143], v[194:197], v[28:31]
	v_mfma_f32_16x16x32_bf16 v[24:27], v[154:157], v[194:197], v[24:27]
	v_mfma_f32_16x16x32_bf16 v[12:15], v[140:143], v[202:205], v[12:15]
	v_mfma_f32_16x16x32_bf16 v[8:11], v[154:157], v[202:205], v[8:11]
	v_mfma_f32_16x16x32_bf16 v[60:63], v[150:153], v[182:185], v[60:63]
	v_mfma_f32_16x16x32_bf16 v[56:59], v[158:161], v[182:185], v[56:59]
	v_mfma_f32_16x16x32_bf16 v[44:47], v[150:153], v[190:193], v[44:47]
	v_mfma_f32_16x16x32_bf16 v[40:43], v[158:161], v[190:193], v[40:43]
	v_mfma_f32_16x16x32_bf16 v[28:31], v[150:153], v[198:201], v[28:31]
	v_mfma_f32_16x16x32_bf16 v[24:27], v[158:161], v[198:201], v[24:27]
	v_mfma_f32_16x16x32_bf16 v[12:15], v[150:153], v[208:211], v[12:15]
	v_mfma_f32_16x16x32_bf16 v[8:11], v[158:161], v[208:211], v[8:11]
	v_mfma_f32_16x16x32_bf16 v[52:55], v[162:165], v[178:181], v[52:55]
	v_mfma_f32_16x16x32_bf16 v[48:51], v[170:173], v[178:181], v[48:51]
	v_mfma_f32_16x16x32_bf16 v[36:39], v[162:165], v[186:189], v[36:39]
	v_mfma_f32_16x16x32_bf16 v[32:35], v[170:173], v[186:189], v[32:35]
	v_mfma_f32_16x16x32_bf16 v[20:23], v[162:165], v[194:197], v[20:23]
	v_mfma_f32_16x16x32_bf16 v[16:19], v[170:173], v[194:197], v[16:19]
	v_mfma_f32_16x16x32_bf16 v[4:7], v[162:165], v[202:205], v[4:7]
	v_mfma_f32_16x16x32_bf16 v[0:3], v[170:173], v[202:205], v[0:3]
	v_mfma_f32_16x16x32_bf16 v[52:55], v[166:169], v[182:185], v[52:55]
	v_mfma_f32_16x16x32_bf16 v[48:51], v[174:177], v[182:185], v[48:51]
	v_mfma_f32_16x16x32_bf16 v[36:39], v[166:169], v[190:193], v[36:39]
	v_mfma_f32_16x16x32_bf16 v[32:35], v[174:177], v[190:193], v[32:35]
	v_mfma_f32_16x16x32_bf16 v[20:23], v[166:169], v[198:201], v[20:23]
	v_mfma_f32_16x16x32_bf16 v[16:19], v[174:177], v[198:201], v[16:19]
	v_mfma_f32_16x16x32_bf16 v[4:7], v[166:169], v[208:211], v[4:7]
	v_mfma_f32_16x16x32_bf16 v[0:3], v[174:177], v[208:211], v[0:3]
	s_barrier
	s_cbranch_scc0 .LBB0_606
	s_setprio 0
	s_and_b64 vcc, exec, s[16:17]
	s_cbranch_vccz .LBB0_609
	s_barrier

.Lbal_last_19:
	ds_read_b128 v[184:187], v153 offset:49152
	ds_read_b128 v[188:191], v153 offset:50176
	ds_read_b128 v[192:195], v153 offset:51200
	ds_read_b128 v[196:199], v153 offset:52224
	ds_read_b128 v[200:203], v153 offset:53248
	ds_read_b128 v[208:211], v153 offset:54272
	ds_read_b128 v[212:215], v153 offset:55296
	ds_read_b128 v[216:219], v153 offset:56320
	s_waitcnt vmcnt(6)
	s_waitcnt lgkmcnt(0)
	s_barrier
	s_waitcnt lgkmcnt(0)
	v_mfma_f32_16x16x32_bf16 v[60:63], v[144:147], v[184:187], v[60:63]
	v_mfma_f32_16x16x32_bf16 v[56:59], v[160:163], v[184:187], v[56:59]
	v_mfma_f32_16x16x32_bf16 v[44:47], v[144:147], v[192:195], v[44:47]
	v_mfma_f32_16x16x32_bf16 v[40:43], v[160:163], v[192:195], v[40:43]
	s_add_i32 s53, s53, 2
	s_add_u32 s51, s51, 0x100
	s_addc_u32 s52, s52, 0
	s_add_u32 s26, s26, 0x100
	s_addc_u32 s27, s27, 0
	s_cmp_gt_u32 s53, 13
	v_mfma_f32_16x16x32_bf16 v[28:31], v[144:147], v[200:203], v[28:31]
	v_mfma_f32_16x16x32_bf16 v[24:27], v[160:163], v[200:203], v[24:27]
	v_mfma_f32_16x16x32_bf16 v[12:15], v[144:147], v[212:215], v[12:15]
	v_mfma_f32_16x16x32_bf16 v[8:11], v[160:163], v[212:215], v[8:11]
	v_mfma_f32_16x16x32_bf16 v[60:63], v[156:159], v[188:191], v[60:63]
	v_mfma_f32_16x16x32_bf16 v[56:59], v[164:167], v[188:191], v[56:59]
	v_mfma_f32_16x16x32_bf16 v[44:47], v[156:159], v[196:199], v[44:47]
	v_mfma_f32_16x16x32_bf16 v[40:43], v[164:167], v[196:199], v[40:43]
	v_mfma_f32_16x16x32_bf16 v[28:31], v[156:159], v[208:211], v[28:31]
	v_mfma_f32_16x16x32_bf16 v[24:27], v[164:167], v[208:211], v[24:27]
	v_mfma_f32_16x16x32_bf16 v[12:15], v[156:159], v[216:219], v[12:15]
	v_mfma_f32_16x16x32_bf16 v[8:11], v[164:167], v[216:219], v[8:11]
	v_mfma_f32_16x16x32_bf16 v[52:55], v[168:171], v[184:187], v[52:55]
	v_mfma_f32_16x16x32_bf16 v[48:51], v[176:179], v[184:187], v[48:51]
	v_mfma_f32_16x16x32_bf16 v[36:39], v[168:171], v[192:195], v[36:39]
	v_mfma_f32_16x16x32_bf16 v[32:35], v[176:179], v[192:195], v[32:35]
	v_mfma_f32_16x16x32_bf16 v[20:23], v[168:171], v[200:203], v[20:23]
	v_mfma_f32_16x16x32_bf16 v[16:19], v[176:179], v[200:203], v[16:19]
	v_mfma_f32_16x16x32_bf16 v[4:7], v[168:171], v[212:215], v[4:7]
	v_mfma_f32_16x16x32_bf16 v[0:3], v[176:179], v[212:215], v[0:3]
	v_mfma_f32_16x16x32_bf16 v[52:55], v[172:175], v[188:191], v[52:55]
	v_mfma_f32_16x16x32_bf16 v[48:51], v[180:183], v[188:191], v[48:51]
	v_mfma_f32_16x16x32_bf16 v[36:39], v[172:175], v[196:199], v[36:39]
	v_mfma_f32_16x16x32_bf16 v[32:35], v[180:183], v[196:199], v[32:35]
	v_mfma_f32_16x16x32_bf16 v[20:23], v[172:175], v[208:211], v[20:23]
	v_mfma_f32_16x16x32_bf16 v[16:19], v[180:183], v[208:211], v[16:19]
	v_mfma_f32_16x16x32_bf16 v[4:7], v[172:175], v[216:219], v[4:7]
	v_mfma_f32_16x16x32_bf16 v[0:3], v[180:183], v[216:219], v[0:3]
	s_barrier
	s_cbranch_scc0 .LBB0_699
	s_setprio 0
	s_and_b64 vcc, exec, s[16:17]
	s_cbranch_vccz .LBB0_702
	s_barrier

.Lbal_last_18:
	ds_read_b128 v[178:181], v149 offset:49152
	ds_read_b128 v[182:185], v149 offset:50176
	ds_read_b128 v[186:189], v149 offset:51200
	ds_read_b128 v[190:193], v149 offset:52224
	ds_read_b128 v[194:197], v149 offset:53248
	ds_read_b128 v[198:201], v149 offset:54272
	ds_read_b128 v[202:205], v149 offset:55296
	ds_read_b128 v[208:211], v149 offset:56320
	s_waitcnt vmcnt(6)
	s_waitcnt lgkmcnt(0)
	s_barrier
	s_waitcnt lgkmcnt(0)
	v_mfma_f32_16x16x32_bf16 v[60:63], v[140:143], v[178:181], v[60:63]
	v_mfma_f32_16x16x32_bf16 v[56:59], v[154:157], v[178:181], v[56:59]
	v_mfma_f32_16x16x32_bf16 v[44:47], v[140:143], v[186:189], v[44:47]
	v_mfma_f32_16x16x32_bf16 v[40:43], v[154:157], v[186:189], v[40:43]
	s_add_i32 s58, s58, 2
	s_add_u32 s56, s56, 0x100
	s_addc_u32 s57, s57, 0
	s_cmp_gt_u32 s58, 61
	s_mov_b64 s[28:29], s[30:31]
	v_mfma_f32_16x16x32_bf16 v[28:31], v[140:143], v[194:197], v[28:31]
	v_mfma_f32_16x16x32_bf16 v[24:27], v[154:157], v[194:197], v[24:27]
	v_mfma_f32_16x16x32_bf16 v[12:15], v[140:143], v[202:205], v[12:15]
	v_mfma_f32_16x16x32_bf16 v[8:11], v[154:157], v[202:205], v[8:11]
	v_mfma_f32_16x16x32_bf16 v[60:63], v[150:153], v[182:185], v[60:63]
	v_mfma_f32_16x16x32_bf16 v[56:59], v[158:161], v[182:185], v[56:59]
	v_mfma_f32_16x16x32_bf16 v[44:47], v[150:153], v[190:193], v[44:47]
	v_mfma_f32_16x16x32_bf16 v[40:43], v[158:161], v[190:193], v[40:43]
	v_mfma_f32_16x16x32_bf16 v[28:31], v[150:153], v[198:201], v[28:31]
	v_mfma_f32_16x16x32_bf16 v[24:27], v[158:161], v[198:201], v[24:27]
	v_mfma_f32_16x16x32_bf16 v[12:15], v[150:153], v[208:211], v[12:15]
	v_mfma_f32_16x16x32_bf16 v[8:11], v[158:161], v[208:211], v[8:11]
	v_mfma_f32_16x16x32_bf16 v[52:55], v[162:165], v[178:181], v[52:55]
	v_mfma_f32_16x16x32_bf16 v[48:51], v[170:173], v[178:181], v[48:51]
	v_mfma_f32_16x16x32_bf16 v[36:39], v[162:165], v[186:189], v[36:39]
	v_mfma_f32_16x16x32_bf16 v[32:35], v[170:173], v[186:189], v[32:35]
	v_mfma_f32_16x16x32_bf16 v[20:23], v[162:165], v[194:197], v[20:23]
	v_mfma_f32_16x16x32_bf16 v[16:19], v[170:173], v[194:197], v[16:19]
	v_mfma_f32_16x16x32_bf16 v[4:7], v[162:165], v[202:205], v[4:7]
	v_mfma_f32_16x16x32_bf16 v[0:3], v[170:173], v[202:205], v[0:3]
	v_mfma_f32_16x16x32_bf16 v[52:55], v[166:169], v[182:185], v[52:55]
	v_mfma_f32_16x16x32_bf16 v[48:51], v[174:177], v[182:185], v[48:51]
	v_mfma_f32_16x16x32_bf16 v[36:39], v[166:169], v[190:193], v[36:39]
	v_mfma_f32_16x16x32_bf16 v[32:35], v[174:177], v[190:193], v[32:35]
	v_mfma_f32_16x16x32_bf16 v[20:23], v[166:169], v[198:201], v[20:23]
	v_mfma_f32_16x16x32_bf16 v[16:19], v[174:177], v[198:201], v[16:19]
	v_mfma_f32_16x16x32_bf16 v[4:7], v[166:169], v[208:211], v[4:7]
	v_mfma_f32_16x16x32_bf16 v[0:3], v[174:177], v[208:211], v[0:3]
	s_barrier
	s_cbranch_scc0 .LBB0_778
	s_setprio 0
	s_and_b64 vcc, exec, s[16:17]
	s_cbranch_vccz .LBB0_781
	s_barrier

.Lbal_last_17:
	ds_read_b128 v[182:185], v155 offset:49152
	ds_read_b128 v[186:189], v155 offset:50176
	ds_read_b128 v[190:193], v155 offset:51200
	ds_read_b128 v[194:197], v155 offset:52224
	ds_read_b128 v[198:201], v155 offset:53248
	ds_read_b128 v[202:205], v155 offset:54272
	ds_read_b128 v[208:211], v155 offset:55296
	ds_read_b128 v[212:215], v155 offset:56320
	s_waitcnt vmcnt(6)
	s_waitcnt lgkmcnt(0)
	s_barrier
	s_waitcnt lgkmcnt(0)
	v_mfma_f32_16x16x32_bf16 v[60:63], v[140:143], v[182:185], v[60:63]
	v_mfma_f32_16x16x32_bf16 v[56:59], v[158:161], v[182:185], v[56:59]
	v_mfma_f32_16x16x32_bf16 v[44:47], v[140:143], v[190:193], v[44:47]
	v_mfma_f32_16x16x32_bf16 v[40:43], v[158:161], v[190:193], v[40:43]
	s_add_i32 s61, s61, 2
	s_add_u32 s59, s59, 0x100
	s_addc_u32 s60, s60, 0
	s_add_u32 s36, s36, 0x100
	s_addc_u32 s37, s37, 0
	s_cmp_gt_u32 s61, 13
	v_mfma_f32_16x16x32_bf16 v[28:31], v[140:143], v[198:201], v[28:31]
	v_mfma_f32_16x16x32_bf16 v[24:27], v[158:161], v[198:201], v[24:27]
	v_mfma_f32_16x16x32_bf16 v[12:15], v[140:143], v[208:211], v[12:15]
	v_mfma_f32_16x16x32_bf16 v[8:11], v[158:161], v[208:211], v[8:11]
	v_mfma_f32_16x16x32_bf16 v[60:63], v[144:147], v[186:189], v[60:63]
	v_mfma_f32_16x16x32_bf16 v[56:59], v[162:165], v[186:189], v[56:59]
	v_mfma_f32_16x16x32_bf16 v[44:47], v[144:147], v[194:197], v[44:47]
	v_mfma_f32_16x16x32_bf16 v[40:43], v[162:165], v[194:197], v[40:43]
	v_mfma_f32_16x16x32_bf16 v[28:31], v[144:147], v[202:205], v[28:31]
	v_mfma_f32_16x16x32_bf16 v[24:27], v[162:165], v[202:205], v[24:27]
	v_mfma_f32_16x16x32_bf16 v[12:15], v[144:147], v[212:215], v[12:15]
	v_mfma_f32_16x16x32_bf16 v[8:11], v[162:165], v[212:215], v[8:11]
	v_mfma_f32_16x16x32_bf16 v[52:55], v[166:169], v[182:185], v[52:55]
	v_mfma_f32_16x16x32_bf16 v[48:51], v[174:177], v[182:185], v[48:51]
	v_mfma_f32_16x16x32_bf16 v[36:39], v[166:169], v[190:193], v[36:39]
	v_mfma_f32_16x16x32_bf16 v[32:35], v[174:177], v[190:193], v[32:35]
	v_mfma_f32_16x16x32_bf16 v[20:23], v[166:169], v[198:201], v[20:23]
	v_mfma_f32_16x16x32_bf16 v[16:19], v[174:177], v[198:201], v[16:19]
	v_mfma_f32_16x16x32_bf16 v[4:7], v[166:169], v[208:211], v[4:7]
	v_mfma_f32_16x16x32_bf16 v[0:3], v[174:177], v[208:211], v[0:3]
	v_mfma_f32_16x16x32_bf16 v[52:55], v[170:173], v[186:189], v[52:55]
	v_mfma_f32_16x16x32_bf16 v[48:51], v[178:181], v[186:189], v[48:51]
	v_mfma_f32_16x16x32_bf16 v[36:39], v[170:173], v[194:197], v[36:39]
	v_mfma_f32_16x16x32_bf16 v[32:35], v[178:181], v[194:197], v[32:35]
	v_mfma_f32_16x16x32_bf16 v[20:23], v[170:173], v[202:205], v[20:23]
	v_mfma_f32_16x16x32_bf16 v[16:19], v[178:181], v[202:205], v[16:19]
	v_mfma_f32_16x16x32_bf16 v[4:7], v[170:173], v[212:215], v[4:7]
	v_mfma_f32_16x16x32_bf16 v[0:3], v[178:181], v[212:215], v[0:3]
	s_barrier
	s_cbranch_scc0 .LBB0_895
	s_setprio 0
	s_and_b64 vcc, exec, s[24:25]
	s_cbranch_vccz .LBB0_898
	s_barrier

.Lbal_last_16:
	ds_read_b128 v[184:187], v153 offset:49152
	ds_read_b128 v[188:191], v153 offset:50176
	ds_read_b128 v[192:195], v153 offset:51200
	ds_read_b128 v[196:199], v153 offset:52224
	ds_read_b128 v[200:203], v153 offset:53248
	ds_read_b128 v[208:211], v153 offset:54272
	ds_read_b128 v[212:215], v153 offset:55296
	ds_read_b128 v[216:219], v153 offset:56320
	s_waitcnt vmcnt(6)
	s_waitcnt lgkmcnt(0)
	s_barrier
	s_waitcnt lgkmcnt(0)
	v_mfma_f32_16x16x32_bf16 v[60:63], v[144:147], v[184:187], v[60:63]
	v_mfma_f32_16x16x32_bf16 v[56:59], v[160:163], v[184:187], v[56:59]
	v_mfma_f32_16x16x32_bf16 v[44:47], v[144:147], v[192:195], v[44:47]
	v_mfma_f32_16x16x32_bf16 v[40:43], v[160:163], v[192:195], v[40:43]
	s_add_i32 s53, s53, 2
	s_add_u32 s51, s51, 0x100
	s_addc_u32 s52, s52, 0
	s_add_u32 s6, s6, 0x100
	s_addc_u32 s7, s7, 0
	s_cmp_gt_u32 s53, 13
	v_mfma_f32_16x16x32_bf16 v[28:31], v[144:147], v[200:203], v[28:31]
	v_mfma_f32_16x16x32_bf16 v[24:27], v[160:163], v[200:203], v[24:27]
	v_mfma_f32_16x16x32_bf16 v[12:15], v[144:147], v[212:215], v[12:15]
	v_mfma_f32_16x16x32_bf16 v[8:11], v[160:163], v[212:215], v[8:11]
	v_mfma_f32_16x16x32_bf16 v[60:63], v[156:159], v[188:191], v[60:63]
	v_mfma_f32_16x16x32_bf16 v[56:59], v[164:167], v[188:191], v[56:59]
	v_mfma_f32_16x16x32_bf16 v[44:47], v[156:159], v[196:199], v[44:47]
	v_mfma_f32_16x16x32_bf16 v[40:43], v[164:167], v[196:199], v[40:43]
	v_mfma_f32_16x16x32_bf16 v[28:31], v[156:159], v[208:211], v[28:31]
	v_mfma_f32_16x16x32_bf16 v[24:27], v[164:167], v[208:211], v[24:27]
	v_mfma_f32_16x16x32_bf16 v[12:15], v[156:159], v[216:219], v[12:15]
	v_mfma_f32_16x16x32_bf16 v[8:11], v[164:167], v[216:219], v[8:11]
	v_mfma_f32_16x16x32_bf16 v[52:55], v[168:171], v[184:187], v[52:55]
	v_mfma_f32_16x16x32_bf16 v[48:51], v[176:179], v[184:187], v[48:51]
	v_mfma_f32_16x16x32_bf16 v[36:39], v[168:171], v[192:195], v[36:39]
	v_mfma_f32_16x16x32_bf16 v[32:35], v[176:179], v[192:195], v[32:35]
	v_mfma_f32_16x16x32_bf16 v[20:23], v[168:171], v[200:203], v[20:23]
	v_mfma_f32_16x16x32_bf16 v[16:19], v[176:179], v[200:203], v[16:19]
	v_mfma_f32_16x16x32_bf16 v[4:7], v[168:171], v[212:215], v[4:7]
	v_mfma_f32_16x16x32_bf16 v[0:3], v[176:179], v[212:215], v[0:3]
	v_mfma_f32_16x16x32_bf16 v[52:55], v[172:175], v[188:191], v[52:55]
	v_mfma_f32_16x16x32_bf16 v[48:51], v[180:183], v[188:191], v[48:51]
	v_mfma_f32_16x16x32_bf16 v[36:39], v[172:175], v[196:199], v[36:39]
	v_mfma_f32_16x16x32_bf16 v[32:35], v[180:183], v[196:199], v[32:35]
	v_mfma_f32_16x16x32_bf16 v[20:23], v[172:175], v[208:211], v[20:23]
	v_mfma_f32_16x16x32_bf16 v[16:19], v[180:183], v[208:211], v[16:19]
	v_mfma_f32_16x16x32_bf16 v[4:7], v[172:175], v[216:219], v[4:7]
	v_mfma_f32_16x16x32_bf16 v[0:3], v[180:183], v[216:219], v[0:3]
	s_barrier
	s_cbranch_scc0 .LBB0_988
	s_setprio 0
	s_and_b64 vcc, exec, s[14:15]
	s_cbranch_vccz .LBB0_991
	s_barrier

.Lbal_last_15:
	ds_read_b128 v[182:185], v153 offset:49152
	ds_read_b128 v[186:189], v153 offset:50176
	ds_read_b128 v[190:193], v153 offset:51200
	ds_read_b128 v[194:197], v153 offset:52224
	ds_read_b128 v[198:201], v153 offset:53248
	ds_read_b128 v[202:205], v153 offset:54272
	ds_read_b128 v[208:211], v153 offset:55296
	ds_read_b128 v[212:215], v153 offset:56320
	s_waitcnt vmcnt(6)
	s_waitcnt lgkmcnt(0)
	s_barrier
	s_waitcnt lgkmcnt(0)
	v_mfma_f32_16x16x32_bf16 v[60:63], v[144:147], v[182:185], v[60:63]
	v_mfma_f32_16x16x32_bf16 v[56:59], v[158:161], v[182:185], v[56:59]
	v_mfma_f32_16x16x32_bf16 v[44:47], v[144:147], v[190:193], v[44:47]
	v_mfma_f32_16x16x32_bf16 v[40:43], v[158:161], v[190:193], v[40:43]
	s_add_i32 s50, s50, 2
	s_add_u32 s48, s48, 0x100
	s_addc_u32 s49, s49, 0
	s_add_u32 s24, s24, 0x100
	s_addc_u32 s25, s25, 0
	s_cmp_gt_u32 s50, 5
	v_mfma_f32_16x16x32_bf16 v[28:31], v[144:147], v[198:201], v[28:31]
	v_mfma_f32_16x16x32_bf16 v[24:27], v[158:161], v[198:201], v[24:27]
	v_mfma_f32_16x16x32_bf16 v[12:15], v[144:147], v[208:211], v[12:15]
	v_mfma_f32_16x16x32_bf16 v[8:11], v[158:161], v[208:211], v[8:11]
	v_mfma_f32_16x16x32_bf16 v[60:63], v[154:157], v[186:189], v[60:63]
	v_mfma_f32_16x16x32_bf16 v[56:59], v[162:165], v[186:189], v[56:59]
	v_mfma_f32_16x16x32_bf16 v[44:47], v[154:157], v[194:197], v[44:47]
	v_mfma_f32_16x16x32_bf16 v[40:43], v[162:165], v[194:197], v[40:43]
	v_mfma_f32_16x16x32_bf16 v[28:31], v[154:157], v[202:205], v[28:31]
	v_mfma_f32_16x16x32_bf16 v[24:27], v[162:165], v[202:205], v[24:27]
	v_mfma_f32_16x16x32_bf16 v[12:15], v[154:157], v[212:215], v[12:15]
	v_mfma_f32_16x16x32_bf16 v[8:11], v[162:165], v[212:215], v[8:11]
	v_mfma_f32_16x16x32_bf16 v[52:55], v[166:169], v[182:185], v[52:55]
	v_mfma_f32_16x16x32_bf16 v[48:51], v[174:177], v[182:185], v[48:51]
	v_mfma_f32_16x16x32_bf16 v[36:39], v[166:169], v[190:193], v[36:39]
	v_mfma_f32_16x16x32_bf16 v[32:35], v[174:177], v[190:193], v[32:35]
	v_mfma_f32_16x16x32_bf16 v[20:23], v[166:169], v[198:201], v[20:23]
	v_mfma_f32_16x16x32_bf16 v[16:19], v[174:177], v[198:201], v[16:19]
	v_mfma_f32_16x16x32_bf16 v[4:7], v[166:169], v[208:211], v[4:7]
	v_mfma_f32_16x16x32_bf16 v[0:3], v[174:177], v[208:211], v[0:3]
	v_mfma_f32_16x16x32_bf16 v[52:55], v[170:173], v[186:189], v[52:55]
	v_mfma_f32_16x16x32_bf16 v[48:51], v[178:181], v[186:189], v[48:51]
	v_mfma_f32_16x16x32_bf16 v[36:39], v[170:173], v[194:197], v[36:39]
	v_mfma_f32_16x16x32_bf16 v[32:35], v[178:181], v[194:197], v[32:35]
	v_mfma_f32_16x16x32_bf16 v[20:23], v[170:173], v[202:205], v[20:23]
	v_mfma_f32_16x16x32_bf16 v[16:19], v[178:181], v[202:205], v[16:19]
	v_mfma_f32_16x16x32_bf16 v[4:7], v[170:173], v[212:215], v[4:7]
	v_mfma_f32_16x16x32_bf16 v[0:3], v[178:181], v[212:215], v[0:3]
	s_barrier
	s_cbranch_scc0 .LBB0_1193
	s_setprio 0
	s_and_b64 vcc, exec, s[12:13]
	s_cbranch_vccz .LBB0_1196
	s_barrier

.Lbal_last_13:
	ds_read_b128 v[184:187], v153 offset:49152
	ds_read_b128 v[188:191], v153 offset:50176
	ds_read_b128 v[192:195], v153 offset:51200
	ds_read_b128 v[196:199], v153 offset:52224
	ds_read_b128 v[200:203], v153 offset:53248
	ds_read_b128 v[208:211], v153 offset:54272
	ds_read_b128 v[212:215], v153 offset:55296
	ds_read_b128 v[216:219], v153 offset:56320
	s_waitcnt vmcnt(6)
	s_waitcnt lgkmcnt(0)
	s_barrier
	s_waitcnt lgkmcnt(0)
	v_mfma_f32_16x16x32_bf16 v[60:63], v[144:147], v[184:187], v[60:63]
	v_mfma_f32_16x16x32_bf16 v[56:59], v[160:163], v[184:187], v[56:59]
	v_mfma_f32_16x16x32_bf16 v[44:47], v[144:147], v[192:195], v[44:47]
	v_mfma_f32_16x16x32_bf16 v[40:43], v[160:163], v[192:195], v[40:43]
	s_add_i32 s53, s53, 2
	s_add_u32 s51, s51, 0x100
	s_addc_u32 s52, s52, 0
	s_add_u32 s24, s24, 0x100
	s_addc_u32 s25, s25, 0
	s_cmp_gt_u32 s53, 13
	v_mfma_f32_16x16x32_bf16 v[28:31], v[144:147], v[200:203], v[28:31]
	v_mfma_f32_16x16x32_bf16 v[24:27], v[160:163], v[200:203], v[24:27]
	v_mfma_f32_16x16x32_bf16 v[12:15], v[144:147], v[212:215], v[12:15]
	v_mfma_f32_16x16x32_bf16 v[8:11], v[160:163], v[212:215], v[8:11]
	v_mfma_f32_16x16x32_bf16 v[60:63], v[156:159], v[188:191], v[60:63]
	v_mfma_f32_16x16x32_bf16 v[56:59], v[164:167], v[188:191], v[56:59]
	v_mfma_f32_16x16x32_bf16 v[44:47], v[156:159], v[196:199], v[44:47]
	v_mfma_f32_16x16x32_bf16 v[40:43], v[164:167], v[196:199], v[40:43]
	v_mfma_f32_16x16x32_bf16 v[28:31], v[156:159], v[208:211], v[28:31]
	v_mfma_f32_16x16x32_bf16 v[24:27], v[164:167], v[208:211], v[24:27]
	v_mfma_f32_16x16x32_bf16 v[12:15], v[156:159], v[216:219], v[12:15]
	v_mfma_f32_16x16x32_bf16 v[8:11], v[164:167], v[216:219], v[8:11]
	v_mfma_f32_16x16x32_bf16 v[52:55], v[168:171], v[184:187], v[52:55]
	v_mfma_f32_16x16x32_bf16 v[48:51], v[176:179], v[184:187], v[48:51]
	v_mfma_f32_16x16x32_bf16 v[36:39], v[168:171], v[192:195], v[36:39]
	v_mfma_f32_16x16x32_bf16 v[32:35], v[176:179], v[192:195], v[32:35]
	v_mfma_f32_16x16x32_bf16 v[20:23], v[168:171], v[200:203], v[20:23]
	v_mfma_f32_16x16x32_bf16 v[16:19], v[176:179], v[200:203], v[16:19]
	v_mfma_f32_16x16x32_bf16 v[4:7], v[168:171], v[212:215], v[4:7]
	v_mfma_f32_16x16x32_bf16 v[0:3], v[176:179], v[212:215], v[0:3]
	v_mfma_f32_16x16x32_bf16 v[52:55], v[172:175], v[188:191], v[52:55]
	v_mfma_f32_16x16x32_bf16 v[48:51], v[180:183], v[188:191], v[48:51]
	v_mfma_f32_16x16x32_bf16 v[36:39], v[172:175], v[196:199], v[36:39]
	v_mfma_f32_16x16x32_bf16 v[32:35], v[180:183], v[196:199], v[32:35]
	v_mfma_f32_16x16x32_bf16 v[20:23], v[172:175], v[208:211], v[20:23]
	v_mfma_f32_16x16x32_bf16 v[16:19], v[180:183], v[208:211], v[16:19]
	v_mfma_f32_16x16x32_bf16 v[4:7], v[172:175], v[216:219], v[4:7]
	v_mfma_f32_16x16x32_bf16 v[0:3], v[180:183], v[216:219], v[0:3]
	s_barrier
	s_cbranch_scc0 .LBB0_1365
	s_setprio 0
	s_and_b64 vcc, exec, s[14:15]
	s_cbranch_vccz .LBB0_1368
	s_barrier

.Lbal_last_11:
	ds_read_b128 v[180:183], v153 offset:49152
	ds_read_b128 v[184:187], v153 offset:50176
	ds_read_b128 v[188:191], v153 offset:51200
	ds_read_b128 v[192:195], v153 offset:52224
	ds_read_b128 v[196:199], v153 offset:53248
	ds_read_b128 v[200:203], v153 offset:54272
	ds_read_b128 v[208:211], v153 offset:55296
	ds_read_b128 v[212:215], v153 offset:56320
	s_waitcnt vmcnt(6)
	s_waitcnt lgkmcnt(0)
	s_barrier
	s_waitcnt lgkmcnt(0)
	v_mfma_f32_16x16x32_bf16 v[60:63], v[140:143], v[180:183], v[60:63]
	v_mfma_f32_16x16x32_bf16 v[56:59], v[156:159], v[180:183], v[56:59]
	v_mfma_f32_16x16x32_bf16 v[44:47], v[140:143], v[188:191], v[44:47]
	v_mfma_f32_16x16x32_bf16 v[40:43], v[156:159], v[188:191], v[40:43]
	s_add_i32 s61, s61, 2
	s_add_u32 s59, s59, 0x100
	s_addc_u32 s60, s60, 0
	s_add_u32 s36, s36, 0x100
	s_addc_u32 s37, s37, 0
	s_cmp_gt_u32 s61, 13
	v_mfma_f32_16x16x32_bf16 v[28:31], v[140:143], v[196:199], v[28:31]
	v_mfma_f32_16x16x32_bf16 v[24:27], v[156:159], v[196:199], v[24:27]
	v_mfma_f32_16x16x32_bf16 v[12:15], v[140:143], v[208:211], v[12:15]
	v_mfma_f32_16x16x32_bf16 v[8:11], v[156:159], v[208:211], v[8:11]
	v_mfma_f32_16x16x32_bf16 v[60:63], v[144:147], v[184:187], v[60:63]
	v_mfma_f32_16x16x32_bf16 v[56:59], v[160:163], v[184:187], v[56:59]
	v_mfma_f32_16x16x32_bf16 v[44:47], v[144:147], v[192:195], v[44:47]
	v_mfma_f32_16x16x32_bf16 v[40:43], v[160:163], v[192:195], v[40:43]
	v_mfma_f32_16x16x32_bf16 v[28:31], v[144:147], v[200:203], v[28:31]
	v_mfma_f32_16x16x32_bf16 v[24:27], v[160:163], v[200:203], v[24:27]
	v_mfma_f32_16x16x32_bf16 v[12:15], v[144:147], v[212:215], v[12:15]
	v_mfma_f32_16x16x32_bf16 v[8:11], v[160:163], v[212:215], v[8:11]
	v_mfma_f32_16x16x32_bf16 v[52:55], v[164:167], v[180:183], v[52:55]
	v_mfma_f32_16x16x32_bf16 v[48:51], v[172:175], v[180:183], v[48:51]
	v_mfma_f32_16x16x32_bf16 v[36:39], v[164:167], v[188:191], v[36:39]
	v_mfma_f32_16x16x32_bf16 v[32:35], v[172:175], v[188:191], v[32:35]
	v_mfma_f32_16x16x32_bf16 v[20:23], v[164:167], v[196:199], v[20:23]
	v_mfma_f32_16x16x32_bf16 v[16:19], v[172:175], v[196:199], v[16:19]
	v_mfma_f32_16x16x32_bf16 v[4:7], v[164:167], v[208:211], v[4:7]
	v_mfma_f32_16x16x32_bf16 v[0:3], v[172:175], v[208:211], v[0:3]
	v_mfma_f32_16x16x32_bf16 v[52:55], v[168:171], v[184:187], v[52:55]
	v_mfma_f32_16x16x32_bf16 v[48:51], v[176:179], v[184:187], v[48:51]
	v_mfma_f32_16x16x32_bf16 v[36:39], v[168:171], v[192:195], v[36:39]
	v_mfma_f32_16x16x32_bf16 v[32:35], v[176:179], v[192:195], v[32:35]
	v_mfma_f32_16x16x32_bf16 v[20:23], v[168:171], v[200:203], v[20:23]
	v_mfma_f32_16x16x32_bf16 v[16:19], v[176:179], v[200:203], v[16:19]
	v_mfma_f32_16x16x32_bf16 v[4:7], v[168:171], v[212:215], v[4:7]
	v_mfma_f32_16x16x32_bf16 v[0:3], v[176:179], v[212:215], v[0:3]
	s_barrier
	s_cbranch_scc0 .LBB0_1561
	s_setprio 0
	s_and_b64 vcc, exec, s[24:25]
	s_cbranch_vccz .LBB0_1564
	s_barrier

.Lbal_last_10:
	ds_read_b128 v[184:187], v153 offset:49152
	ds_read_b128 v[188:191], v153 offset:50176
	ds_read_b128 v[192:195], v153 offset:51200
	ds_read_b128 v[196:199], v153 offset:52224
	ds_read_b128 v[200:203], v153 offset:53248
	ds_read_b128 v[208:211], v153 offset:54272
	ds_read_b128 v[212:215], v153 offset:55296
	ds_read_b128 v[216:219], v153 offset:56320
	s_waitcnt vmcnt(6)
	s_waitcnt lgkmcnt(0)
	s_barrier
	s_waitcnt lgkmcnt(0)
	v_mfma_f32_16x16x32_bf16 v[60:63], v[144:147], v[184:187], v[60:63]
	v_mfma_f32_16x16x32_bf16 v[56:59], v[160:163], v[184:187], v[56:59]
	v_mfma_f32_16x16x32_bf16 v[44:47], v[144:147], v[192:195], v[44:47]
	v_mfma_f32_16x16x32_bf16 v[40:43], v[160:163], v[192:195], v[40:43]
	s_add_i32 s54, s54, 2
	s_add_u32 s52, s52, 0x100
	s_addc_u32 s53, s53, 0
	s_add_u32 s24, s24, 0x100
	s_addc_u32 s25, s25, 0
	s_cmp_gt_u32 s54, 13
	v_mfma_f32_16x16x32_bf16 v[28:31], v[144:147], v[200:203], v[28:31]
	v_mfma_f32_16x16x32_bf16 v[24:27], v[160:163], v[200:203], v[24:27]
	v_mfma_f32_16x16x32_bf16 v[12:15], v[144:147], v[212:215], v[12:15]
	v_mfma_f32_16x16x32_bf16 v[8:11], v[160:163], v[212:215], v[8:11]
	v_mfma_f32_16x16x32_bf16 v[60:63], v[156:159], v[188:191], v[60:63]
	v_mfma_f32_16x16x32_bf16 v[56:59], v[164:167], v[188:191], v[56:59]
	v_mfma_f32_16x16x32_bf16 v[44:47], v[156:159], v[196:199], v[44:47]
	v_mfma_f32_16x16x32_bf16 v[40:43], v[164:167], v[196:199], v[40:43]
	v_mfma_f32_16x16x32_bf16 v[28:31], v[156:159], v[208:211], v[28:31]
	v_mfma_f32_16x16x32_bf16 v[24:27], v[164:167], v[208:211], v[24:27]
	v_mfma_f32_16x16x32_bf16 v[12:15], v[156:159], v[216:219], v[12:15]
	v_mfma_f32_16x16x32_bf16 v[8:11], v[164:167], v[216:219], v[8:11]
	v_mfma_f32_16x16x32_bf16 v[52:55], v[168:171], v[184:187], v[52:55]
	v_mfma_f32_16x16x32_bf16 v[48:51], v[176:179], v[184:187], v[48:51]
	v_mfma_f32_16x16x32_bf16 v[36:39], v[168:171], v[192:195], v[36:39]
	v_mfma_f32_16x16x32_bf16 v[32:35], v[176:179], v[192:195], v[32:35]
	v_mfma_f32_16x16x32_bf16 v[20:23], v[168:171], v[200:203], v[20:23]
	v_mfma_f32_16x16x32_bf16 v[16:19], v[176:179], v[200:203], v[16:19]
	v_mfma_f32_16x16x32_bf16 v[4:7], v[168:171], v[212:215], v[4:7]
	v_mfma_f32_16x16x32_bf16 v[0:3], v[176:179], v[212:215], v[0:3]
	v_mfma_f32_16x16x32_bf16 v[52:55], v[172:175], v[188:191], v[52:55]
	v_mfma_f32_16x16x32_bf16 v[48:51], v[180:183], v[188:191], v[48:51]
	v_mfma_f32_16x16x32_bf16 v[36:39], v[172:175], v[196:199], v[36:39]
	v_mfma_f32_16x16x32_bf16 v[32:35], v[180:183], v[196:199], v[32:35]
	v_mfma_f32_16x16x32_bf16 v[20:23], v[172:175], v[208:211], v[20:23]
	v_mfma_f32_16x16x32_bf16 v[16:19], v[180:183], v[208:211], v[16:19]
	v_mfma_f32_16x16x32_bf16 v[4:7], v[172:175], v[216:219], v[4:7]
	v_mfma_f32_16x16x32_bf16 v[0:3], v[180:183], v[216:219], v[0:3]
	s_barrier
	s_cbranch_scc0 .LBB0_1646
	s_setprio 0
	s_and_b64 vcc, exec, s[14:15]
	s_cbranch_vccz .LBB0_1649
	s_barrier
